# MLA second-tile exp consumers (row-sum adds + bf16 pack) delayed by one group with alternating temp pairs, giving each v_exp a full MFMA slot before its first use
# speedup vs baseline: 1.0096x; 1.0096x over previous
.LBB0_546:
	s_or_b64 exec, exec, s[24:25]
	global_load_dwordx4 v[206:209], v[252:253], off
	s_mov_b64 s[0:1], 0x10000
	v_lshl_add_u64 v[250:251], v[250:251], 0, s[0:1]
	v_lshl_add_u64 v[252:253], v[252:253], 0, s[0:1]
	v_exp_f32_e32 v0, v82
	v_exp_f32_e32 v34, v83
	v_mfma_f32_32x32x16_bf16 v[114:129], v[98:101], v[150:153], v[66:81]
	v_exp_f32_e32 v36, v85
	v_add_f32_e32 v35, v34, v0
	v_cvt_pk_bf16_f32 v34, v0, v34
	v_exp_f32_e32 v0, v84
	s_nop 0
	v_add_f32_e32 v35, v0, v35
	v_add_f32_e32 v37, v36, v35
	v_cvt_pk_bf16_f32 v35, v0, v36
	v_exp_f32_e32 v0, v86
	v_mfma_f32_32x32x16_bf16 v[98:113], v[202:205], v[150:153], v[66:81]
	v_exp_f32_e32 v36, v87
	v_exp_f32_e32 v38, v88
	v_exp_f32_e32 v39, v89
	v_add_f32_e32 v37, v0, v37
	v_add_f32_e32 v37, v36, v37
	v_cvt_pk_bf16_f32 v36, v0, v36
	v_add_f32_e32 v0, v38, v37
	v_add_f32_e32 v0, v39, v0
	v_cvt_pk_bf16_f32 v37, v38, v39
	v_exp_f32_e32 v38, v90
	v_exp_f32_e32 v39, v91
	v_mfma_f32_32x32x16_bf16 v[114:129], v[198:201], v[146:149], v[114:129]
	v_exp_f32_e32 v40, v93
	v_add_f32_e32 v0, v38, v0
	v_add_f32_e32 v0, v39, v0
	v_cvt_pk_bf16_f32 v38, v38, v39
	v_exp_f32_e32 v39, v92
	s_nop 0
	v_add_f32_e32 v0, v39, v0
	v_add_f32_e32 v0, v40, v0
	v_cvt_pk_bf16_f32 v39, v39, v40
	v_exp_f32_e32 v40, v94
	v_exp_f32_e32 v41, v95
	v_mfma_f32_32x32x16_bf16 v[98:113], v[194:197], v[146:149], v[98:113]
	v_exp_f32_e32 v42, v97
	v_add_f32_e32 v0, v40, v0
	v_add_f32_e32 v0, v41, v0
	v_cvt_pk_bf16_f32 v40, v40, v41
	v_exp_f32_e32 v41, v96
	s_nop 0
	v_add_f32_e32 v0, v41, v0
	v_add_f32_e32 v0, v42, v0
	v_cvt_pk_bf16_f32 v41, v41, v42
	v_mfma_f32_32x32x16_bf16 v[114:129], v[190:193], v[142:145], v[114:129]
	ds_read_b64_tr_b16 v[82:83], v231 offset:26624
	ds_read_b64_tr_b16 v[84:85], v231 offset:27392
	ds_read_b64_tr_b16 v[46:47], v231 offset:26688
	ds_read_b64_tr_b16 v[48:49], v231 offset:27456
	v_exp_f32_e32 v236, v50
	v_exp_f32_e32 v237, v51
	v_mfma_f32_32x32x16_bf16 v[98:113], v[186:189], v[142:145], v[98:113]
	v_exp_f32_e32 v218, v52
	v_exp_f32_e32 v219, v53
	ds_read_b64_tr_b16 v[86:87], v231 offset:29696
	ds_read_b64_tr_b16 v[88:89], v231 offset:30464
	v_add_f32_e32 v0, v236, v0
	v_add_f32_e32 v0, v237, v0
	v_cvt_pk_bf16_f32 v42, v236, v237
	v_mfma_f32_32x32x16_bf16 v[114:129], v[182:185], v[138:141], v[114:129]
	v_exp_f32_e32 v236, v54
	v_exp_f32_e32 v237, v55
	ds_read_b64_tr_b16 v[90:91], v231 offset:29760
	ds_read_b64_tr_b16 v[92:93], v231 offset:30528
	v_add_f32_e32 v0, v218, v0
	v_add_f32_e32 v0, v219, v0
	v_cvt_pk_bf16_f32 v43, v218, v219
	v_mfma_f32_32x32x16_bf16 v[98:113], v[178:181], v[138:141], v[98:113]
	v_exp_f32_e32 v218, v56
	v_exp_f32_e32 v219, v57
	ds_read_b64_tr_b16 v[94:95], v231 offset:32768
	ds_read_b64_tr_b16 v[96:97], v231 offset:33536
	v_add_f32_e32 v0, v236, v0
	v_add_f32_e32 v0, v237, v0
	v_cvt_pk_bf16_f32 v44, v236, v237
	v_mfma_f32_32x32x16_bf16 v[114:129], v[174:177], v[134:137], v[114:129]
	v_exp_f32_e32 v236, v58
	v_exp_f32_e32 v237, v59
	ds_read_b64_tr_b16 v[210:211], v231 offset:32832
	ds_read_b64_tr_b16 v[212:213], v231 offset:33600
	v_add_f32_e32 v0, v218, v0
	v_add_f32_e32 v0, v219, v0
	v_cvt_pk_bf16_f32 v45, v218, v219
	v_mfma_f32_32x32x16_bf16 v[98:113], v[170:173], v[134:137], v[98:113]
	v_exp_f32_e32 v218, v60
	v_exp_f32_e32 v219, v61
	ds_read_b64_tr_b16 v[58:59], v231 offset:35840
	ds_read_b64_tr_b16 v[60:61], v231 offset:36608
	v_add_f32_e32 v0, v236, v0
	v_add_f32_e32 v0, v237, v0
	v_cvt_pk_bf16_f32 v54, v236, v237
	v_mfma_f32_32x32x16_bf16 v[114:129], v[166:169], v[130:133], v[114:129]
	v_exp_f32_e32 v236, v62
	v_exp_f32_e32 v237, v63
	ds_read_b64_tr_b16 v[214:215], v231 offset:35904
	ds_read_b64_tr_b16 v[216:217], v231 offset:36672
	v_add_f32_e32 v0, v218, v0
	v_add_f32_e32 v0, v219, v0
	v_cvt_pk_bf16_f32 v55, v218, v219
	v_mfma_f32_32x32x16_bf16 v[98:113], v[158:161], v[130:133], v[98:113]
	v_exp_f32_e32 v218, v64
	v_exp_f32_e32 v219, v65
	v_add_f32_e32 v0, v236, v0
	v_add_f32_e32 v0, v237, v0
	v_cvt_pk_bf16_f32 v56, v236, v237
	v_add_f32_e32 v0, v218, v0
	v_add_f32_e32 v62, v219, v0
	v_cvt_pk_bf16_f32 v57, v218, v219
	s_waitcnt lgkmcnt(14)
	v_mfma_f32_32x32x16_bf16 v[18:33], v[82:85], v[34:37], v[18:33]
	ds_read_b128 v[50:53], v233
	ds_read_b128 v[198:201], v233 offset:6656
	v_add_f32_e32 v0, v242, v62
	s_waitcnt lgkmcnt(14)
	v_mfma_f32_32x32x16_bf16 v[2:17], v[46:49], v[34:37], v[2:17]
	ds_read_b128 v[202:205], v233 offset:32
	ds_read_b128 v[194:197], v233 offset:6688
	s_waitcnt lgkmcnt(14)
	v_mfma_f32_32x32x16_bf16 v[18:33], v[86:89], v[38:41], v[18:33]
	ds_read_b128 v[190:193], v233 offset:64
	ds_read_b128 v[186:189], v233 offset:6720
	s_waitcnt lgkmcnt(14)
	v_mfma_f32_32x32x16_bf16 v[2:17], v[90:93], v[38:41], v[2:17]
	ds_read_b128 v[182:185], v233 offset:96
	ds_read_b128 v[178:181], v233 offset:6752
	s_waitcnt lgkmcnt(14)
	v_mfma_f32_32x32x16_bf16 v[18:33], v[94:97], v[42:45], v[18:33]
	ds_read_b128 v[174:177], v233 offset:128
	ds_read_b128 v[170:173], v233 offset:6784
	s_waitcnt lgkmcnt(14)
	v_mfma_f32_32x32x16_bf16 v[2:17], v[210:213], v[42:45], v[2:17]
	ds_read_b128 v[166:169], v233 offset:160
	ds_read_b128 v[158:161], v233 offset:6816
	s_waitcnt lgkmcnt(14)
	v_mfma_f32_32x32x16_bf16 v[18:33], v[58:61], v[54:57], v[18:33]
	s_waitcnt lgkmcnt(12)
	v_mfma_f32_32x32x16_bf16 v[2:17], v[214:217], v[54:57], v[2:17]
	v_mov_b32_e32 v34, v62
	s_nop 1
	v_permlane32_swap_b32_e32 v62, v34
	v_max_f32_e32 v34, v62, v34
	v_cmp_lt_f32_e32 vcc, s74, v34
	s_cbranch_vccz .LBB0_558
	v_frexp_exp_i32_f32_e32 v34, v34
	v_cvt_f32_i32_e32 v34, v34
	v_cndmask_b32_e32 v35, 0, v34, vcc
	v_exp_f32_e64 v36, -v35
	v_add_f32_e32 v235, v235, v35
	v_xor_b32_e32 v34, 0x80000000, v235
	v_sub_f32_e32 v129, v129, v35
	v_pk_mul_f32 v[32:33], v[32:33], v[36:37] op_sel_hi:[1,0]
	v_pk_mul_f32 v[30:31], v[30:31], v[36:37] op_sel_hi:[1,0]
	v_pk_mul_f32 v[28:29], v[28:29], v[36:37] op_sel_hi:[1,0]
	v_pk_mul_f32 v[26:27], v[26:27], v[36:37] op_sel_hi:[1,0]
	v_pk_mul_f32 v[24:25], v[24:25], v[36:37] op_sel_hi:[1,0]
	v_pk_mul_f32 v[22:23], v[22:23], v[36:37] op_sel_hi:[1,0]
	v_pk_mul_f32 v[20:21], v[20:21], v[36:37] op_sel_hi:[1,0]
	v_pk_mul_f32 v[18:19], v[18:19], v[36:37] op_sel_hi:[1,0]
	v_pk_mul_f32 v[16:17], v[16:17], v[36:37] op_sel_hi:[1,0]
	v_pk_mul_f32 v[14:15], v[14:15], v[36:37] op_sel_hi:[1,0]
	v_pk_mul_f32 v[12:13], v[12:13], v[36:37] op_sel_hi:[1,0]
	v_pk_mul_f32 v[10:11], v[10:11], v[36:37] op_sel_hi:[1,0]
	v_pk_mul_f32 v[8:9], v[8:9], v[36:37] op_sel_hi:[1,0]
	v_pk_mul_f32 v[6:7], v[6:7], v[36:37] op_sel_hi:[1,0]
	v_pk_mul_f32 v[4:5], v[4:5], v[36:37] op_sel_hi:[1,0]
	v_pk_mul_f32 v[2:3], v[2:3], v[36:37] op_sel_hi:[1,0]
	v_sub_f32_e32 v128, v128, v35
	v_sub_f32_e32 v127, v127, v35
	v_sub_f32_e32 v126, v126, v35
	v_sub_f32_e32 v125, v125, v35
	v_sub_f32_e32 v124, v124, v35
	v_sub_f32_e32 v123, v123, v35
	v_sub_f32_e32 v122, v122, v35
	v_sub_f32_e32 v121, v121, v35
	v_sub_f32_e32 v120, v120, v35
	v_sub_f32_e32 v119, v119, v35
	v_sub_f32_e32 v118, v118, v35
	v_sub_f32_e32 v117, v117, v35
	v_sub_f32_e32 v116, v116, v35
	v_sub_f32_e32 v115, v115, v35
	v_sub_f32_e32 v114, v114, v35
	v_sub_f32_e32 v113, v113, v35
	v_sub_f32_e32 v112, v112, v35
	v_sub_f32_e32 v111, v111, v35
	v_sub_f32_e32 v110, v110, v35
	v_sub_f32_e32 v109, v109, v35
	v_sub_f32_e32 v108, v108, v35
	v_sub_f32_e32 v107, v107, v35
	v_sub_f32_e32 v106, v106, v35
	v_sub_f32_e32 v105, v105, v35
	v_sub_f32_e32 v104, v104, v35
	v_sub_f32_e32 v103, v103, v35
	v_sub_f32_e32 v102, v102, v35
	v_sub_f32_e32 v101, v101, v35
	v_sub_f32_e32 v100, v100, v35
	v_sub_f32_e32 v99, v99, v35
	v_sub_f32_e32 v98, v98, v35
	v_mul_f32_e32 v0, v0, v36
	v_mov_b32_e32 v35, v34
	v_mov_b32_e32 v36, v34
	v_mov_b32_e32 v37, v34
	v_mov_b32_e32 v38, v34
	v_mov_b32_e32 v39, v34
	v_mov_b32_e32 v40, v34
	v_mov_b32_e32 v41, v34
	v_mov_b32_e32 v42, v34
	v_mov_b32_e32 v43, v34
	v_mov_b32_e32 v44, v34
	v_mov_b32_e32 v45, v34
	v_mov_b32_e32 v46, v34
	v_mov_b32_e32 v47, v34
	v_mov_b32_e32 v48, v34
	v_mov_b32_e32 v49, v34
	v_mov_b32_e32 v66, v34
	v_mov_b32_e32 v67, v34
	v_mov_b32_e32 v68, v34
	v_mov_b32_e32 v69, v34
	v_mov_b32_e32 v70, v34
	v_mov_b32_e32 v71, v34
	v_mov_b32_e32 v72, v34
	v_mov_b32_e32 v73, v34
	v_mov_b32_e32 v74, v34
	v_mov_b32_e32 v75, v34
	v_mov_b32_e32 v76, v34
	v_mov_b32_e32 v77, v34
	v_mov_b32_e32 v78, v34
	v_mov_b32_e32 v79, v34
	v_mov_b32_e32 v80, v34
	v_mov_b32_e32 v81, v34
	s_waitcnt vmcnt(1)
	ds_write_b128 v232, v[162:165] offset:13312
	s_and_saveexec_b64 s[24:25], s[4:5]

.LBB0_553:
	global_load_dwordx4 v[206:209], v[252:253], off
	s_mov_b64 s[0:1], 0x10000
	v_lshl_add_u64 v[250:251], v[250:251], 0, s[0:1]
	v_lshl_add_u64 v[252:253], v[252:253], 0, s[0:1]
	v_mfma_f32_32x32x16_bf16 v[82:97], v[50:53], v[150:153], v[66:81]
	v_exp_f32_e32 v50, v114
	v_exp_f32_e32 v51, v115
	v_add_f32_e32 v52, 0, v50
	v_cvt_pk_bf16_f32 v114, v50, v51
	v_exp_f32_e32 v50, v116
	v_add_f32_e32 v52, v51, v52
	v_exp_f32_e32 v51, v117
	v_add_f32_e32 v52, v50, v52
	v_add_f32_e32 v52, v51, v52
	v_cvt_pk_bf16_f32 v115, v50, v51
	v_exp_f32_e32 v116, v118
	v_exp_f32_e32 v117, v119
	v_exp_f32_e32 v118, v120
	v_exp_f32_e32 v119, v121
	v_add_f32_e32 v50, v116, v52
	v_add_f32_e32 v120, v117, v50
	v_mfma_f32_32x32x16_bf16 v[50:65], v[198:201], v[150:153], v[66:81]
	v_cvt_pk_bf16_f32 v116, v116, v117
	v_add_f32_e32 v117, v118, v120
	v_add_f32_e32 v120, v119, v117
	v_cvt_pk_bf16_f32 v117, v118, v119
	v_exp_f32_e32 v118, v122
	v_exp_f32_e32 v119, v123
	v_mfma_f32_32x32x16_bf16 v[82:97], v[202:205], v[146:149], v[82:97]
	v_exp_f32_e32 v121, v125
	v_add_f32_e32 v120, v118, v120
	v_add_f32_e32 v120, v119, v120
	v_cvt_pk_bf16_f32 v118, v118, v119
	v_exp_f32_e32 v119, v124
	s_nop 0
	v_add_f32_e32 v120, v119, v120
	v_add_f32_e32 v120, v121, v120
	v_cvt_pk_bf16_f32 v119, v119, v121
	v_exp_f32_e32 v121, v126
	v_exp_f32_e32 v122, v127
	v_mfma_f32_32x32x16_bf16 v[50:65], v[194:197], v[146:149], v[50:65]
	v_add_f32_e32 v120, v121, v120
	v_add_f32_e32 v123, v122, v120
	v_cvt_pk_bf16_f32 v120, v121, v122
	v_exp_f32_e32 v121, v128
	v_exp_f32_e32 v122, v129
	v_add_f32_e32 v123, v121, v123
	v_add_f32_e32 v123, v122, v123
	v_cvt_pk_bf16_f32 v121, v121, v122
	v_mfma_f32_32x32x16_bf16 v[82:97], v[190:193], v[142:145], v[82:97]
	ds_read_b64_tr_b16 v[190:191], v231 offset:38912
	ds_read_b64_tr_b16 v[192:193], v231 offset:39680
	ds_read_b64_tr_b16 v[126:127], v231 offset:38976
	ds_read_b64_tr_b16 v[128:129], v231 offset:39744
	v_exp_f32_e32 v98, v98
	v_exp_f32_e32 v99, v99
	v_mfma_f32_32x32x16_bf16 v[50:65], v[186:189], v[142:145], v[50:65]
	v_exp_f32_e32 v218, v100
	v_exp_f32_e32 v219, v101
	ds_read_b64_tr_b16 v[186:187], v231 offset:41984
	ds_read_b64_tr_b16 v[188:189], v231 offset:42752
	v_add_f32_e32 v236, v98, v123
	v_add_f32_e32 v236, v99, v236
	v_cvt_pk_bf16_f32 v122, v98, v99
	v_mfma_f32_32x32x16_bf16 v[82:97], v[182:185], v[138:141], v[82:97]
	v_exp_f32_e32 v98, v102
	v_exp_f32_e32 v99, v103
	ds_read_b64_tr_b16 v[182:183], v231 offset:42048
	ds_read_b64_tr_b16 v[184:185], v231 offset:42816
	v_add_f32_e32 v236, v218, v236
	v_add_f32_e32 v236, v219, v236
	v_cvt_pk_bf16_f32 v123, v218, v219
	v_mfma_f32_32x32x16_bf16 v[50:65], v[178:181], v[138:141], v[50:65]
	v_exp_f32_e32 v218, v104
	v_exp_f32_e32 v219, v105
	ds_read_b64_tr_b16 v[210:211], v231 offset:45056
	ds_read_b64_tr_b16 v[212:213], v231 offset:45824
	v_add_f32_e32 v236, v98, v236
	v_add_f32_e32 v236, v99, v236
	v_cvt_pk_bf16_f32 v124, v98, v99
	v_mfma_f32_32x32x16_bf16 v[82:97], v[174:177], v[134:137], v[82:97]
	v_exp_f32_e32 v98, v106
	v_exp_f32_e32 v99, v107
	ds_read_b64_tr_b16 v[214:215], v231 offset:45120
	ds_read_b64_tr_b16 v[216:217], v231 offset:45888
	v_add_f32_e32 v236, v218, v236
	v_add_f32_e32 v236, v219, v236
	v_cvt_pk_bf16_f32 v125, v218, v219
	v_mfma_f32_32x32x16_bf16 v[50:65], v[170:173], v[134:137], v[50:65]
	v_exp_f32_e32 v218, v108
	v_exp_f32_e32 v219, v109
	ds_read_b64_tr_b16 v[106:107], v231 offset:48128
	ds_read_b64_tr_b16 v[108:109], v231 offset:48896
	v_add_f32_e32 v236, v98, v236
	v_add_f32_e32 v236, v99, v236
	v_cvt_pk_bf16_f32 v102, v98, v99
	v_mfma_f32_32x32x16_bf16 v[82:97], v[166:169], v[130:133], v[82:97]
	v_exp_f32_e32 v98, v110
	v_exp_f32_e32 v99, v111
	ds_read_b64_tr_b16 v[244:245], v231 offset:48192
	ds_read_b64_tr_b16 v[246:247], v231 offset:48960
	v_add_f32_e32 v236, v218, v236
	v_add_f32_e32 v236, v219, v236
	v_cvt_pk_bf16_f32 v103, v218, v219
	v_mfma_f32_32x32x16_bf16 v[50:65], v[158:161], v[130:133], v[50:65]
	v_exp_f32_e32 v218, v112
	v_exp_f32_e32 v219, v113
	v_add_f32_e32 v236, v98, v236
	v_add_f32_e32 v236, v99, v236
	v_cvt_pk_bf16_f32 v104, v98, v99
	v_add_f32_e32 v236, v218, v236
	v_add_f32_e32 v110, v219, v236
	v_cvt_pk_bf16_f32 v105, v218, v219
	s_waitcnt lgkmcnt(14)
	v_mfma_f32_32x32x16_bf16 v[18:33], v[190:193], v[114:117], v[18:33]
	ds_read_b128 v[98:101], v233 offset:13312
	ds_read_b128 v[202:205], v233 offset:19968
	v_add_f32_e32 v242, v0, v110
	s_waitcnt lgkmcnt(14)
	v_mfma_f32_32x32x16_bf16 v[2:17], v[126:129], v[114:117], v[2:17]
	ds_read_b128 v[198:201], v233 offset:13344
	ds_read_b128 v[194:197], v233 offset:20000
	s_waitcnt lgkmcnt(14)
	v_mfma_f32_32x32x16_bf16 v[18:33], v[186:189], v[118:121], v[18:33]
	ds_read_b128 v[190:193], v233 offset:13376
	ds_read_b128 v[186:189], v233 offset:20032
	s_waitcnt lgkmcnt(14)
	v_mfma_f32_32x32x16_bf16 v[2:17], v[182:185], v[118:121], v[2:17]
	ds_read_b128 v[182:185], v233 offset:13408
	ds_read_b128 v[178:181], v233 offset:20064
	s_waitcnt lgkmcnt(14)
	v_mfma_f32_32x32x16_bf16 v[18:33], v[210:213], v[122:125], v[18:33]
	ds_read_b128 v[174:177], v233 offset:13440
	ds_read_b128 v[170:173], v233 offset:20096
	s_waitcnt lgkmcnt(14)
	v_mfma_f32_32x32x16_bf16 v[2:17], v[214:217], v[122:125], v[2:17]
	ds_read_b128 v[166:169], v233 offset:13472
	ds_read_b128 v[158:161], v233 offset:20128
	s_waitcnt lgkmcnt(14)
	v_mfma_f32_32x32x16_bf16 v[18:33], v[106:109], v[102:105], v[18:33]
	s_waitcnt lgkmcnt(12)
	v_mfma_f32_32x32x16_bf16 v[2:17], v[244:247], v[102:105], v[2:17]
	v_mov_b32_e32 v0, v110
	s_nop 1
	v_permlane32_swap_b32_e32 v110, v0
	v_max_f32_e32 v0, v110, v0
	v_cmp_lt_f32_e32 vcc, s74, v0
	s_cbranch_vccz .LBB0_555
	v_frexp_exp_i32_f32_e32 v0, v0
	v_cvt_f32_i32_e32 v0, v0
	v_cndmask_b32_e32 v35, 0, v0, vcc
	v_exp_f32_e64 v0, -v35
	v_add_f32_e32 v235, v235, v35
	v_xor_b32_e32 v34, 0x80000000, v235
	v_sub_f32_e32 v97, v97, v35
	v_pk_mul_f32 v[32:33], v[32:33], v[0:1] op_sel_hi:[1,0]
	v_pk_mul_f32 v[30:31], v[30:31], v[0:1] op_sel_hi:[1,0]
	v_pk_mul_f32 v[28:29], v[28:29], v[0:1] op_sel_hi:[1,0]
	v_pk_mul_f32 v[26:27], v[26:27], v[0:1] op_sel_hi:[1,0]
	v_pk_mul_f32 v[24:25], v[24:25], v[0:1] op_sel_hi:[1,0]
	v_pk_mul_f32 v[22:23], v[22:23], v[0:1] op_sel_hi:[1,0]
	v_pk_mul_f32 v[20:21], v[20:21], v[0:1] op_sel_hi:[1,0]
	v_pk_mul_f32 v[18:19], v[18:19], v[0:1] op_sel_hi:[1,0]
	v_pk_mul_f32 v[16:17], v[16:17], v[0:1] op_sel_hi:[1,0]
	v_pk_mul_f32 v[14:15], v[14:15], v[0:1] op_sel_hi:[1,0]
	v_pk_mul_f32 v[12:13], v[12:13], v[0:1] op_sel_hi:[1,0]
	v_pk_mul_f32 v[10:11], v[10:11], v[0:1] op_sel_hi:[1,0]
	v_pk_mul_f32 v[8:9], v[8:9], v[0:1] op_sel_hi:[1,0]
	v_pk_mul_f32 v[6:7], v[6:7], v[0:1] op_sel_hi:[1,0]
	v_pk_mul_f32 v[4:5], v[4:5], v[0:1] op_sel_hi:[1,0]
	v_pk_mul_f32 v[2:3], v[2:3], v[0:1] op_sel_hi:[1,0]
	v_sub_f32_e32 v96, v96, v35
	v_sub_f32_e32 v95, v95, v35
	v_sub_f32_e32 v94, v94, v35
	v_sub_f32_e32 v93, v93, v35
	v_sub_f32_e32 v92, v92, v35
	v_sub_f32_e32 v91, v91, v35
	v_sub_f32_e32 v90, v90, v35
	v_sub_f32_e32 v89, v89, v35
	v_sub_f32_e32 v88, v88, v35
	v_sub_f32_e32 v87, v87, v35
	v_sub_f32_e32 v86, v86, v35
	v_sub_f32_e32 v85, v85, v35
	v_sub_f32_e32 v84, v84, v35
	v_sub_f32_e32 v83, v83, v35
	v_sub_f32_e32 v82, v82, v35
	v_sub_f32_e32 v65, v65, v35
	v_sub_f32_e32 v64, v64, v35
	v_sub_f32_e32 v63, v63, v35
	v_sub_f32_e32 v62, v62, v35
	v_sub_f32_e32 v61, v61, v35
	v_sub_f32_e32 v60, v60, v35
	v_sub_f32_e32 v59, v59, v35
	v_sub_f32_e32 v58, v58, v35
	v_sub_f32_e32 v57, v57, v35
	v_sub_f32_e32 v56, v56, v35
	v_sub_f32_e32 v55, v55, v35
	v_sub_f32_e32 v54, v54, v35
	v_sub_f32_e32 v53, v53, v35
	v_sub_f32_e32 v52, v52, v35
	v_sub_f32_e32 v51, v51, v35
	v_sub_f32_e32 v50, v50, v35
	v_mul_f32_e32 v242, v242, v0
	v_mov_b32_e32 v35, v34
	v_mov_b32_e32 v36, v34
	v_mov_b32_e32 v37, v34
	v_mov_b32_e32 v38, v34
	v_mov_b32_e32 v39, v34
	v_mov_b32_e32 v40, v34
	v_mov_b32_e32 v41, v34
	v_mov_b32_e32 v42, v34
	v_mov_b32_e32 v43, v34
	v_mov_b32_e32 v44, v34
	v_mov_b32_e32 v45, v34
	v_mov_b32_e32 v46, v34
	v_mov_b32_e32 v47, v34
	v_mov_b32_e32 v48, v34
	v_mov_b32_e32 v49, v34
	v_mov_b32_e32 v66, v34
	v_mov_b32_e32 v67, v34
	v_mov_b32_e32 v68, v34
	v_mov_b32_e32 v69, v34
	v_mov_b32_e32 v70, v34
	v_mov_b32_e32 v71, v34
	v_mov_b32_e32 v72, v34
	v_mov_b32_e32 v73, v34
	v_mov_b32_e32 v74, v34
	v_mov_b32_e32 v75, v34
	v_mov_b32_e32 v76, v34
	v_mov_b32_e32 v77, v34
	v_mov_b32_e32 v78, v34
	v_mov_b32_e32 v79, v34
	v_mov_b32_e32 v80, v34
	v_mov_b32_e32 v81, v34
